# per-half A/B of the static priority raise: waves 0..3 get s_setprio 1 in the GEMM K-loops instead of waves 4..7 (flips still deleted; P5 A-fragment read interleave kept)
# speedup vs baseline: 1.0014x; 1.0014x over previous
;     __device__ __forceinline__ long a_off(int pm, size_t tstep) const { return (long)pm * (long)tstep; }
; template <class Epi, class Sched, bool ALIGN_EPI = false, bool SP2 = false>
; __device__ __forceinline__ void gemm_phase(PG8_LAS unsigned char* lds, const Gemm g, const Sched& S, const Epi& E) {
;     ...
;         const bool has_next = S.next(ui + 1, nxt);
;         const char* nA = has_next ? (const char*)g.A + S.a_off(nxt.pm, tstep) : cA; const char* nB = has_next ? (const char*)g.Bt + (size_t)nxt.pn * tstep : cB;
;         for (int t = 0; t < nt; t += 2) {
;             const bool last = (t == nt - 2);
;             const char* a1 = cA + (size_t)(t + 1) * kstep;
;             const char* a2 = last ? nA : cA + (size_t)(t + 2) * kstep; const char* b2 = last ? nB : cB + (size_t)(t + 2) * kstep;
;             const char* a3 = a2 + kstep; const char* b3 = b2 + kstep;
;     ...
; #pragma unroll
;         for (int a = 0; a < 2; ++a)
; #pragma unroll
;             for (int b = 0; b < 2; ++b)
; #pragma unroll
;                 for (int m = 0; m < 4; ++m)
; #pragma unroll
;                     for (int n = 0; n < 2; ++n) acc[a][b][m][n] = (f32x4){0.f, 0.f, 0.f, 0.f};
.LBB0_273:
	s_ashr_i32 s45, s44, 31
	s_lshl_b64 s[46:47], s[44:45], 19
	s_add_u32 s46, s3, s46
	s_addc_u32 s47, s4, s47
	s_and_b64 s[48:49], s[8:9], exec
	s_cselect_b32 s45, s47, s15
	s_cselect_b32 s89, s46, s14
	s_ashr_i32 s43, s42, 31
	s_lshl_b64 s[48:49], s[42:43], 19
	s_add_u32 s48, s5, s48
	s_addc_u32 s49, s28, s49
	s_and_b64 s[52:53], s[8:9], exec
	s_cselect_b32 s43, s49, s51
	s_cselect_b32 s90, s48, s50
	s_add_u32 s14, s14, 0x40080
	s_addc_u32 s15, s15, 0
	s_add_u32 s91, s50, 0x100
	v_mov_b32_e32 v0, 0
	s_addc_u32 s92, s51, 0
	s_mov_b32 s93, -2
	v_mov_b32_e32 v1, v0
	v_mov_b32_e32 v2, v0
	v_mov_b32_e32 v3, v0
	v_mov_b32_e32 v4, v0
	v_mov_b32_e32 v5, v0
	v_mov_b32_e32 v6, v0
	v_mov_b32_e32 v7, v0
	v_mov_b32_e32 v12, v0
	v_mov_b32_e32 v13, v0
	v_mov_b32_e32 v14, v0
	v_mov_b32_e32 v15, v0
	v_mov_b32_e32 v20, v0
	v_mov_b32_e32 v21, v0
	v_mov_b32_e32 v22, v0
	v_mov_b32_e32 v23, v0
	v_mov_b32_e32 v28, v0
	v_mov_b32_e32 v29, v0
	v_mov_b32_e32 v30, v0
	v_mov_b32_e32 v31, v0
	v_mov_b32_e32 v36, v0
	v_mov_b32_e32 v37, v0
	v_mov_b32_e32 v38, v0
	v_mov_b32_e32 v39, v0
	v_mov_b32_e32 v44, v0
	v_mov_b32_e32 v45, v0
	v_mov_b32_e32 v46, v0
	v_mov_b32_e32 v47, v0
	v_mov_b32_e32 v52, v0
	v_mov_b32_e32 v53, v0
	v_mov_b32_e32 v54, v0
	v_mov_b32_e32 v55, v0
	v_mov_b32_e32 v8, v0
	v_mov_b32_e32 v9, v0
	v_mov_b32_e32 v10, v0
	v_mov_b32_e32 v11, v0
	v_mov_b32_e32 v16, v0
	v_mov_b32_e32 v17, v0
	v_mov_b32_e32 v18, v0
	v_mov_b32_e32 v19, v0
	v_mov_b32_e32 v24, v0
	v_mov_b32_e32 v25, v0
	v_mov_b32_e32 v26, v0
	v_mov_b32_e32 v27, v0
	v_mov_b32_e32 v32, v0
	v_mov_b32_e32 v33, v0
	v_mov_b32_e32 v34, v0
	v_mov_b32_e32 v35, v0
	v_mov_b32_e32 v40, v0
	v_mov_b32_e32 v41, v0
	v_mov_b32_e32 v42, v0
	v_mov_b32_e32 v43, v0
	v_mov_b32_e32 v48, v0
	v_mov_b32_e32 v49, v0
	v_mov_b32_e32 v50, v0
	v_mov_b32_e32 v51, v0
	v_mov_b32_e32 v56, v0
	v_mov_b32_e32 v57, v0
	v_mov_b32_e32 v58, v0
	v_mov_b32_e32 v59, v0
	v_mov_b32_e32 v60, v0
	v_mov_b32_e32 v61, v0
	v_mov_b32_e32 v62, v0
	v_mov_b32_e32 v63, v0
	v_mov_b32_e32 v64, v0
	v_mov_b32_e32 v65, v0
	v_mov_b32_e32 v66, v0
	v_mov_b32_e32 v67, v0
	v_mov_b32_e32 v68, v0
	v_mov_b32_e32 v69, v0
	v_mov_b32_e32 v70, v0
	v_mov_b32_e32 v71, v0
	v_mov_b32_e32 v76, v0
	v_mov_b32_e32 v77, v0
	v_mov_b32_e32 v78, v0
	v_mov_b32_e32 v79, v0
	v_mov_b32_e32 v84, v0
	v_mov_b32_e32 v85, v0
	v_mov_b32_e32 v86, v0
	v_mov_b32_e32 v87, v0
	v_mov_b32_e32 v92, v0
	v_mov_b32_e32 v93, v0
	v_mov_b32_e32 v94, v0
	v_mov_b32_e32 v95, v0
	v_mov_b32_e32 v100, v0
	v_mov_b32_e32 v101, v0
	v_mov_b32_e32 v102, v0
	v_mov_b32_e32 v103, v0
	v_mov_b32_e32 v108, v0
	v_mov_b32_e32 v109, v0
	v_mov_b32_e32 v110, v0
	v_mov_b32_e32 v111, v0
	v_mov_b32_e32 v116, v0
	v_mov_b32_e32 v117, v0
	v_mov_b32_e32 v118, v0
	v_mov_b32_e32 v119, v0
	v_mov_b32_e32 v72, v0
	v_mov_b32_e32 v73, v0
	v_mov_b32_e32 v74, v0
	v_mov_b32_e32 v75, v0
	v_mov_b32_e32 v80, v0
	v_mov_b32_e32 v81, v0
	v_mov_b32_e32 v82, v0
	v_mov_b32_e32 v83, v0
	v_mov_b32_e32 v88, v0
	v_mov_b32_e32 v89, v0
	v_mov_b32_e32 v90, v0
	v_mov_b32_e32 v91, v0
	v_mov_b32_e32 v96, v0
	v_mov_b32_e32 v97, v0
	v_mov_b32_e32 v98, v0
	v_mov_b32_e32 v99, v0
	v_mov_b32_e32 v104, v0
	v_mov_b32_e32 v105, v0
	v_mov_b32_e32 v106, v0
	v_mov_b32_e32 v107, v0
	v_mov_b32_e32 v112, v0
	v_mov_b32_e32 v113, v0
	v_mov_b32_e32 v114, v0
	v_mov_b32_e32 v115, v0
	v_mov_b32_e32 v120, v0
	v_mov_b32_e32 v121, v0
	v_mov_b32_e32 v122, v0
	v_mov_b32_e32 v123, v0
	v_mov_b32_e32 v124, v0
	v_mov_b32_e32 v125, v0
	v_mov_b32_e32 v126, v0
	v_mov_b32_e32 v127, v0
	v_readfirstlane_b32 s32, v208
	s_cmp_ge_u32 s32, 256
	s_cbranch_scc1 .Lprio2_done
	s_setprio 1

;     __device__ __forceinline__ long a_off(int pm, size_t tstep) const { return (long)pm * (long)tstep; }
; template <class Epi, class Sched, bool ALIGN_EPI = false, bool SP2 = false>
; __device__ __forceinline__ void gemm_phase(PG8_LAS unsigned char* lds, const Gemm g, const Sched& S, const Epi& E) {
;     ...
;         const bool has_next = S.next(ui + 1, nxt);
;         const char* nA = has_next ? (const char*)g.A + S.a_off(nxt.pm, tstep) : cA; const char* nB = has_next ? (const char*)g.Bt + (size_t)nxt.pn * tstep : cB;
;         for (int t = 0; t < nt; t += 2) {
;             const bool last = (t == nt - 2);
;             const char* a1 = cA + (size_t)(t + 1) * kstep;
;             const char* a2 = last ? nA : cA + (size_t)(t + 2) * kstep; const char* b2 = last ? nB : cB + (size_t)(t + 2) * kstep;
;             const char* a3 = a2 + kstep; const char* b3 = b2 + kstep;
;     ...
; #pragma unroll
;         for (int a = 0; a < 2; ++a)
; #pragma unroll
;             for (int b = 0; b < 2; ++b)
; #pragma unroll
;                 for (int m = 0; m < 4; ++m)
; #pragma unroll
;                     for (int n = 0; n < 2; ++n) acc[a][b][m][n] = (f32x4){0.f, 0.f, 0.f, 0.f};
.LBB0_457:
	s_ashr_i32 s49, s48, 31
	s_lshl_b64 s[50:51], s[48:49], 19
	s_add_u32 s50, s3, s50
	s_addc_u32 s51, s4, s51
	s_and_b64 s[52:53], s[10:11], exec
	s_cselect_b32 s15, s51, s55
	s_cselect_b32 s23, s50, s54
	s_ashr_i32 s47, s46, 31
	s_lshl_b64 s[52:53], s[46:47], 19
	s_add_u32 s52, s5, s52
	s_addc_u32 s53, s6, s53
	s_and_b64 s[58:59], s[10:11], exec
	s_cselect_b32 s47, s53, s57
	s_cselect_b32 s49, s52, s56
	s_add_u32 s54, s54, 0x40080
	s_addc_u32 s55, s55, 0
	s_add_u32 s75, s56, 0x100
	v_mov_b32_e32 v0, 0
	s_addc_u32 s76, s57, 0
	s_mov_b32 s77, -2
	s_waitcnt lgkmcnt(0)
	v_mov_b32_e32 v1, v0
	v_mov_b32_e32 v2, v0
	v_mov_b32_e32 v3, v0
	v_mov_b32_e32 v4, v0
	v_mov_b32_e32 v5, v0
	v_mov_b32_e32 v6, v0
	v_mov_b32_e32 v7, v0
	v_mov_b32_e32 v16, v0
	v_mov_b32_e32 v17, v0
	v_mov_b32_e32 v18, v0
	v_mov_b32_e32 v19, v0
	v_mov_b32_e32 v20, v0
	v_mov_b32_e32 v21, v0
	v_mov_b32_e32 v22, v0
	v_mov_b32_e32 v23, v0
	v_mov_b32_e32 v32, v0
	v_mov_b32_e32 v33, v0
	v_mov_b32_e32 v34, v0
	v_mov_b32_e32 v35, v0
	v_mov_b32_e32 v36, v0
	v_mov_b32_e32 v37, v0
	v_mov_b32_e32 v38, v0
	v_mov_b32_e32 v39, v0
	v_mov_b32_e32 v48, v0
	v_mov_b32_e32 v49, v0
	v_mov_b32_e32 v50, v0
	v_mov_b32_e32 v51, v0
	v_mov_b32_e32 v52, v0
	v_mov_b32_e32 v53, v0
	v_mov_b32_e32 v54, v0
	v_mov_b32_e32 v55, v0
	v_mov_b32_e32 v8, v0
	v_mov_b32_e32 v9, v0
	v_mov_b32_e32 v10, v0
	v_mov_b32_e32 v11, v0
	v_mov_b32_e32 v12, v0
	v_mov_b32_e32 v13, v0
	v_mov_b32_e32 v14, v0
	v_mov_b32_e32 v15, v0
	v_mov_b32_e32 v24, v0
	v_mov_b32_e32 v25, v0
	v_mov_b32_e32 v26, v0
	v_mov_b32_e32 v27, v0
	v_mov_b32_e32 v28, v0
	v_mov_b32_e32 v29, v0
	v_mov_b32_e32 v30, v0
	v_mov_b32_e32 v31, v0
	v_mov_b32_e32 v40, v0
	v_mov_b32_e32 v41, v0
	v_mov_b32_e32 v42, v0
	v_mov_b32_e32 v43, v0
	v_mov_b32_e32 v44, v0
	v_mov_b32_e32 v45, v0
	v_mov_b32_e32 v46, v0
	v_mov_b32_e32 v47, v0
	v_mov_b32_e32 v56, v0
	v_mov_b32_e32 v57, v0
	v_mov_b32_e32 v58, v0
	v_mov_b32_e32 v59, v0
	v_mov_b32_e32 v60, v0
	v_mov_b32_e32 v61, v0
	v_mov_b32_e32 v62, v0
	v_mov_b32_e32 v63, v0
	v_mov_b32_e32 v72, v0
	v_mov_b32_e32 v73, v0
	v_mov_b32_e32 v74, v0
	v_mov_b32_e32 v75, v0
	v_mov_b32_e32 v84, v0
	v_mov_b32_e32 v85, v0
	v_mov_b32_e32 v86, v0
	v_mov_b32_e32 v87, v0
	v_mov_b32_e32 v96, v0
	v_mov_b32_e32 v97, v0
	v_mov_b32_e32 v98, v0
	v_mov_b32_e32 v99, v0
	v_mov_b32_e32 v100, v0
	v_mov_b32_e32 v101, v0
	v_mov_b32_e32 v102, v0
	v_mov_b32_e32 v103, v0
	v_mov_b32_e32 v112, v0
	v_mov_b32_e32 v113, v0
	v_mov_b32_e32 v114, v0
	v_mov_b32_e32 v115, v0
	v_mov_b32_e32 v116, v0
	v_mov_b32_e32 v117, v0
	v_mov_b32_e32 v118, v0
	v_mov_b32_e32 v119, v0
	v_mov_b32_e32 v128, v0
	v_mov_b32_e32 v129, v0
	v_mov_b32_e32 v130, v0
	v_mov_b32_e32 v131, v0
	v_mov_b32_e32 v132, v0
	v_mov_b32_e32 v133, v0
	v_mov_b32_e32 v134, v0
	v_mov_b32_e32 v135, v0
	v_mov_b32_e32 v88, v0
	v_mov_b32_e32 v89, v0
	v_mov_b32_e32 v90, v0
	v_mov_b32_e32 v91, v0
	v_mov_b32_e32 v92, v0
	v_mov_b32_e32 v93, v0
	v_mov_b32_e32 v94, v0
	v_mov_b32_e32 v95, v0
	v_mov_b32_e32 v104, v0
	v_mov_b32_e32 v105, v0
	v_mov_b32_e32 v106, v0
	v_mov_b32_e32 v107, v0
	v_mov_b32_e32 v108, v0
	v_mov_b32_e32 v109, v0
	v_mov_b32_e32 v110, v0
	v_mov_b32_e32 v111, v0
	v_mov_b32_e32 v120, v0
	v_mov_b32_e32 v121, v0
	v_mov_b32_e32 v122, v0
	v_mov_b32_e32 v123, v0
	v_mov_b32_e32 v124, v0
	v_mov_b32_e32 v125, v0
	v_mov_b32_e32 v126, v0
	v_mov_b32_e32 v127, v0
	v_mov_b32_e32 v136, v0
	v_mov_b32_e32 v137, v0
	v_mov_b32_e32 v138, v0
	v_mov_b32_e32 v139, v0
	v_mov_b32_e32 v140, v0
	v_mov_b32_e32 v141, v0
	v_mov_b32_e32 v142, v0
	v_mov_b32_e32 v143, v0
	v_readfirstlane_b32 s32, v208
	s_cmp_ge_u32 s32, 256
	s_cbranch_scc1 .Lprio4_done
	s_setprio 1

;     __device__ __forceinline__ long a_off(int pm, size_t tstep) const { return (long)pm * (long)tstep; }
; template <class Epi, class Sched, bool ALIGN_EPI = false, bool SP2 = false>
; __device__ __forceinline__ void gemm_phase(PG8_LAS unsigned char* lds, const Gemm g, const Sched& S, const Epi& E) {
;     ...
;         const bool has_next = S.next(ui + 1, nxt);
;         const char* nA = has_next ? (const char*)g.A + S.a_off(nxt.pm, tstep) : cA; const char* nB = has_next ? (const char*)g.Bt + (size_t)nxt.pn * tstep : cB;
;         for (int t = 0; t < nt; t += 2) {
;             const bool last = (t == nt - 2);
;             const char* a1 = cA + (size_t)(t + 1) * kstep;
;             const char* a2 = last ? nA : cA + (size_t)(t + 2) * kstep; const char* b2 = last ? nB : cB + (size_t)(t + 2) * kstep;
;             const char* a3 = a2 + kstep; const char* b3 = b2 + kstep;
;     ...
; #pragma unroll
;         for (int a = 0; a < 2; ++a)
; #pragma unroll
;             for (int b = 0; b < 2; ++b)
; #pragma unroll
;                 for (int m = 0; m < 4; ++m)
; #pragma unroll
;                     for (int n = 0; n < 2; ++n) acc[a][b][m][n] = (f32x4){0.f, 0.f, 0.f, 0.f};
.LBB0_573:
	s_ashr_i32 s63, s62, 31
	s_lshl_b64 s[16:17], s[62:63], 19
	s_add_u32 s66, s59, s16
	s_addc_u32 s67, s73, s17
	s_and_b64 s[10:11], s[10:11], exec
	s_cselect_b32 s16, s67, s13
	s_cselect_b32 s17, s66, s12
	s_add_u32 s10, s14, 0x40080
	s_addc_u32 s11, s15, 0
	s_add_u32 s19, s12, 0x100
	v_mov_b32_e32 v96, 0
	s_addc_u32 s20, s13, 0
	s_mov_b32 s21, -2
	v_mov_b32_e32 v97, v96
	v_mov_b32_e32 v98, v96
	v_mov_b32_e32 v99, v96
	v_mov_b32_e32 v100, v96
	v_mov_b32_e32 v101, v96
	v_mov_b32_e32 v102, v96
	v_mov_b32_e32 v103, v96
	v_mov_b32_e32 v0, v96
	v_mov_b32_e32 v1, v96
	v_mov_b32_e32 v2, v96
	v_mov_b32_e32 v3, v96
	v_mov_b32_e32 v48, v96
	v_mov_b32_e32 v49, v96
	v_mov_b32_e32 v50, v96
	v_mov_b32_e32 v51, v96
	v_mov_b32_e32 v8, v96
	v_mov_b32_e32 v9, v96
	v_mov_b32_e32 v10, v96
	v_mov_b32_e32 v11, v96
	v_mov_b32_e32 v56, v96
	v_mov_b32_e32 v57, v96
	v_mov_b32_e32 v58, v96
	v_mov_b32_e32 v59, v96
	v_mov_b32_e32 v16, v96
	v_mov_b32_e32 v17, v96
	v_mov_b32_e32 v18, v96
	v_mov_b32_e32 v19, v96
	v_mov_b32_e32 v64, v96
	v_mov_b32_e32 v65, v96
	v_mov_b32_e32 v66, v96
	v_mov_b32_e32 v67, v96
	v_mov_b32_e32 v104, v96
	v_mov_b32_e32 v105, v96
	v_mov_b32_e32 v106, v96
	v_mov_b32_e32 v107, v96
	v_mov_b32_e32 v108, v96
	v_mov_b32_e32 v109, v96
	v_mov_b32_e32 v110, v96
	v_mov_b32_e32 v111, v96
	v_mov_b32_e32 v4, v96
	v_mov_b32_e32 v5, v96
	v_mov_b32_e32 v6, v96
	v_mov_b32_e32 v7, v96
	v_mov_b32_e32 v52, v96
	v_mov_b32_e32 v53, v96
	v_mov_b32_e32 v54, v96
	v_mov_b32_e32 v55, v96
	v_mov_b32_e32 v12, v96
	v_mov_b32_e32 v13, v96
	v_mov_b32_e32 v14, v96
	v_mov_b32_e32 v15, v96
	v_mov_b32_e32 v60, v96
	v_mov_b32_e32 v61, v96
	v_mov_b32_e32 v62, v96
	v_mov_b32_e32 v63, v96
	v_mov_b32_e32 v20, v96
	v_mov_b32_e32 v21, v96
	v_mov_b32_e32 v22, v96
	v_mov_b32_e32 v23, v96
	v_mov_b32_e32 v68, v96
	v_mov_b32_e32 v69, v96
	v_mov_b32_e32 v70, v96
	v_mov_b32_e32 v71, v96
	v_mov_b32_e32 v112, v96
	v_mov_b32_e32 v113, v96
	v_mov_b32_e32 v114, v96
	v_mov_b32_e32 v115, v96
	v_mov_b32_e32 v116, v96
	v_mov_b32_e32 v117, v96
	v_mov_b32_e32 v118, v96
	v_mov_b32_e32 v119, v96
	v_mov_b32_e32 v24, v96
	v_mov_b32_e32 v25, v96
	v_mov_b32_e32 v26, v96
	v_mov_b32_e32 v27, v96
	v_mov_b32_e32 v72, v96
	v_mov_b32_e32 v73, v96
	v_mov_b32_e32 v74, v96
	v_mov_b32_e32 v75, v96
	v_mov_b32_e32 v32, v96
	v_mov_b32_e32 v33, v96
	v_mov_b32_e32 v34, v96
	v_mov_b32_e32 v35, v96
	v_mov_b32_e32 v80, v96
	v_mov_b32_e32 v81, v96
	v_mov_b32_e32 v82, v96
	v_mov_b32_e32 v83, v96
	v_mov_b32_e32 v40, v96
	v_mov_b32_e32 v41, v96
	v_mov_b32_e32 v42, v96
	v_mov_b32_e32 v43, v96
	v_mov_b32_e32 v88, v96
	v_mov_b32_e32 v89, v96
	v_mov_b32_e32 v90, v96
	v_mov_b32_e32 v91, v96
	v_mov_b32_e32 v120, v96
	v_mov_b32_e32 v121, v96
	v_mov_b32_e32 v122, v96
	v_mov_b32_e32 v123, v96
	v_mov_b32_e32 v124, v96
	v_mov_b32_e32 v125, v96
	v_mov_b32_e32 v126, v96
	v_mov_b32_e32 v127, v96
	v_mov_b32_e32 v28, v96
	v_mov_b32_e32 v29, v96
	v_mov_b32_e32 v30, v96
	v_mov_b32_e32 v31, v96
	v_mov_b32_e32 v76, v96
	v_mov_b32_e32 v77, v96
	v_mov_b32_e32 v78, v96
	v_mov_b32_e32 v79, v96
	v_mov_b32_e32 v36, v96
	v_mov_b32_e32 v37, v96
	v_mov_b32_e32 v38, v96
	v_mov_b32_e32 v39, v96
	v_mov_b32_e32 v84, v96
	v_mov_b32_e32 v85, v96
	v_mov_b32_e32 v86, v96
	v_mov_b32_e32 v87, v96
	v_mov_b32_e32 v44, v96
	v_mov_b32_e32 v45, v96
	v_mov_b32_e32 v46, v96
	v_mov_b32_e32 v47, v96
	v_mov_b32_e32 v92, v96
	v_mov_b32_e32 v93, v96
	v_mov_b32_e32 v94, v96
	v_mov_b32_e32 v95, v96
	v_readfirstlane_b32 s32, v208
	s_cmp_ge_u32 s32, 256
	s_cbranch_scc1 .Lprio5_done
	s_setprio 1

;     __device__ __forceinline__ long a_off(int pm, size_t tstep) const { return (long)pm * (long)tstep; }
; template <class Epi, class Sched, bool ALIGN_EPI = false, bool SP2 = false>
; __device__ __forceinline__ void gemm_phase(PG8_LAS unsigned char* lds, const Gemm g, const Sched& S, const Epi& E) {
;     ...
;         const bool has_next = S.next(ui + 1, nxt);
;         const char* nA = has_next ? (const char*)g.A + S.a_off(nxt.pm, tstep) : cA; const char* nB = has_next ? (const char*)g.Bt + (size_t)nxt.pn * tstep : cB;
;         for (int t = 0; t < nt; t += 2) {
;             const bool last = (t == nt - 2);
;             const char* a1 = cA + (size_t)(t + 1) * kstep;
;             const char* a2 = last ? nA : cA + (size_t)(t + 2) * kstep; const char* b2 = last ? nB : cB + (size_t)(t + 2) * kstep;
;             const char* a3 = a2 + kstep; const char* b3 = b2 + kstep;
;     ...
; #pragma unroll
;         for (int a = 0; a < 2; ++a)
; #pragma unroll
;             for (int b = 0; b < 2; ++b)
; #pragma unroll
;                 for (int m = 0; m < 4; ++m)
; #pragma unroll
;                     for (int n = 0; n < 2; ++n) acc[a][b][m][n] = (f32x4){0.f, 0.f, 0.f, 0.f};
.LBB0_673:
	s_add_u32 s22, s22, 0xb0080
	s_addc_u32 s23, s23, 0
	s_add_u32 s50, s24, 0x100
	v_mov_b32_e32 v0, 0
	s_addc_u32 s51, s25, 0
	s_mov_b32 s52, -2
	v_mov_b32_e32 v1, v0
	v_mov_b32_e32 v2, v0
	v_mov_b32_e32 v3, v0
	v_mov_b32_e32 v4, v0
	v_mov_b32_e32 v5, v0
	v_mov_b32_e32 v6, v0
	v_mov_b32_e32 v7, v0
	v_mov_b32_e32 v12, v0
	v_mov_b32_e32 v13, v0
	v_mov_b32_e32 v14, v0
	v_mov_b32_e32 v15, v0
	v_mov_b32_e32 v20, v0
	v_mov_b32_e32 v21, v0
	v_mov_b32_e32 v22, v0
	v_mov_b32_e32 v23, v0
	v_mov_b32_e32 v28, v0
	v_mov_b32_e32 v29, v0
	v_mov_b32_e32 v30, v0
	v_mov_b32_e32 v31, v0
	v_mov_b32_e32 v36, v0
	v_mov_b32_e32 v37, v0
	v_mov_b32_e32 v38, v0
	v_mov_b32_e32 v39, v0
	v_mov_b32_e32 v44, v0
	v_mov_b32_e32 v45, v0
	v_mov_b32_e32 v46, v0
	v_mov_b32_e32 v47, v0
	v_mov_b32_e32 v52, v0
	v_mov_b32_e32 v53, v0
	v_mov_b32_e32 v54, v0
	v_mov_b32_e32 v55, v0
	v_mov_b32_e32 v8, v0
	v_mov_b32_e32 v9, v0
	v_mov_b32_e32 v10, v0
	v_mov_b32_e32 v11, v0
	v_mov_b32_e32 v16, v0
	v_mov_b32_e32 v17, v0
	v_mov_b32_e32 v18, v0
	v_mov_b32_e32 v19, v0
	v_mov_b32_e32 v24, v0
	v_mov_b32_e32 v25, v0
	v_mov_b32_e32 v26, v0
	v_mov_b32_e32 v27, v0
	v_mov_b32_e32 v32, v0
	v_mov_b32_e32 v33, v0
	v_mov_b32_e32 v34, v0
	v_mov_b32_e32 v35, v0
	v_mov_b32_e32 v40, v0
	v_mov_b32_e32 v41, v0
	v_mov_b32_e32 v42, v0
	v_mov_b32_e32 v43, v0
	v_mov_b32_e32 v48, v0
	v_mov_b32_e32 v49, v0
	v_mov_b32_e32 v50, v0
	v_mov_b32_e32 v51, v0
	v_mov_b32_e32 v56, v0
	v_mov_b32_e32 v57, v0
	v_mov_b32_e32 v58, v0
	v_mov_b32_e32 v59, v0
	v_mov_b32_e32 v60, v0
	v_mov_b32_e32 v61, v0
	v_mov_b32_e32 v62, v0
	v_mov_b32_e32 v63, v0
	v_mov_b32_e32 v64, v0
	v_mov_b32_e32 v65, v0
	v_mov_b32_e32 v66, v0
	v_mov_b32_e32 v67, v0
	v_mov_b32_e32 v68, v0
	v_mov_b32_e32 v69, v0
	v_mov_b32_e32 v70, v0
	v_mov_b32_e32 v71, v0
	v_mov_b32_e32 v76, v0
	v_mov_b32_e32 v77, v0
	v_mov_b32_e32 v78, v0
	v_mov_b32_e32 v79, v0
	v_mov_b32_e32 v84, v0
	v_mov_b32_e32 v85, v0
	v_mov_b32_e32 v86, v0
	v_mov_b32_e32 v87, v0
	v_mov_b32_e32 v92, v0
	v_mov_b32_e32 v93, v0
	v_mov_b32_e32 v94, v0
	v_mov_b32_e32 v95, v0
	v_mov_b32_e32 v100, v0
	v_mov_b32_e32 v101, v0
	v_mov_b32_e32 v102, v0
	v_mov_b32_e32 v103, v0
	v_mov_b32_e32 v104, v0
	v_mov_b32_e32 v105, v0
	v_mov_b32_e32 v106, v0
	v_mov_b32_e32 v107, v0
	v_mov_b32_e32 v108, v0
	v_mov_b32_e32 v109, v0
	v_mov_b32_e32 v110, v0
	v_mov_b32_e32 v111, v0
	v_mov_b32_e32 v72, v0
	v_mov_b32_e32 v73, v0
	v_mov_b32_e32 v74, v0
	v_mov_b32_e32 v75, v0
	v_mov_b32_e32 v80, v0
	v_mov_b32_e32 v81, v0
	v_mov_b32_e32 v82, v0
	v_mov_b32_e32 v83, v0
	v_mov_b32_e32 v88, v0
	v_mov_b32_e32 v89, v0
	v_mov_b32_e32 v90, v0
	v_mov_b32_e32 v91, v0
	v_mov_b32_e32 v96, v0
	v_mov_b32_e32 v97, v0
	v_mov_b32_e32 v98, v0
	v_mov_b32_e32 v99, v0
	v_mov_b32_e32 v112, v0
	v_mov_b32_e32 v113, v0
	v_mov_b32_e32 v114, v0
	v_mov_b32_e32 v115, v0
	v_mov_b32_e32 v116, v0
	v_mov_b32_e32 v117, v0
	v_mov_b32_e32 v118, v0
	v_mov_b32_e32 v119, v0
	v_mov_b32_e32 v120, v0
	v_mov_b32_e32 v121, v0
	v_mov_b32_e32 v122, v0
	v_mov_b32_e32 v123, v0
	v_mov_b32_e32 v124, v0
	v_mov_b32_e32 v125, v0
	v_mov_b32_e32 v126, v0
	v_mov_b32_e32 v127, v0
	v_readfirstlane_b32 s32, v208
	s_cmp_ge_u32 s32, 256
	s_cbranch_scc1 .Lprio7_done
	s_setprio 1
